# w_down recompute epilogue: column slots 1..3 load all eight row groups in one batch (freed accumulators as extra slots): 5 load round trips instead of 8
# speedup vs baseline: 1.0090x; 1.0039x over previous
;     __device__ __forceinline__ void operator()(const f32x4 (&acc)[2][2][4][2], const Unit& u, int wr, int wc, int fr, int fq) const {
;         const int row0 = u.pm * BM + wr * 64 + fr, col0 = u.pn * BM + wc * 32 + 4 * fq;
;         f32x4 gv[2][2];
; #pragma unroll
;         for (int bj = 0; bj < 2; ++bj)
; #pragma unroll
;             for (int n = 0; n < 2; ++n) gv[bj][n] = *(const f32x4*)(gate + col0 + bj * HALF + n * 16) + 1.0f;
; #pragma unroll
;         for (int ai = 0; ai < 2; ++ai)
; #pragma unroll
;             for (int m = 0; m < 4; ++m) { const size_t off = (size_t)(row0 + ai * HALF + m * 16) * ldc + col0;
; #pragma unroll
;                 for (int bj = 0; bj < 2; ++bj)
; #pragma unroll
;                     for (int n = 0; n < 2; ++n) { const f32x4 xr = *(const f32x4*)(xres + off + bj * HALF + n * 16);
;                         *(f32x4*)(z + off + bj * HALF + n * 16) = xr * alpha + gv[bj][n] * acc[ai][bj][m][n]; }
;                 if (m == 3) asm volatile("" ::: "memory"); }
;     }
; __device__ __forceinline__ void phase_ln(const float* z, float* xo, const float* __restrict__ g, const float* __restrict__ b, const float* __restrict__ sc, const float* __restrict__ sh, bf16_t* __restrict__ u) {
;     ...
;                 const f32x4 o = (v[k][j] - mean[k]) * rstd[k] * gg + bb;
.LBB0_1271:
	v_lshl_or_b32 v158, s58, 8, v164
	v_ashrrev_i32_e32 v159, 31, v158
	v_mov_b32_e32 v212, 0x20068
	ds_read2_b64 v[236:239], v212 offset1:1
	v_readlane_b32 s24, v254, 46
	v_lshl_add_u64 v[178:179], v[158:159], 2, s[16:17]
	v_lshl_add_u32 v160, s57, 8, v162
	v_ashrrev_i32_e32 v161, 31, v160
	s_lshl_b32 s24, s24, 11
	s_nop 1
	v_add_u32_e32 v212, s24, v158
	v_mov_b32_e32 v213, 0
	s_sub_u32 s24, s14, 0x10000
	s_subb_u32 s25, s15, 0
	v_lshlrev_b32_e32 v184, 3, v160
	global_load_dwordx2 v[140:141], v184, s[24:25]
	global_load_dwordx2 v[142:143], v184, s[24:25] offset:128
	global_load_dwordx2 v[144:145], v184, s[24:25] offset:256
	global_load_dwordx2 v[146:147], v184, s[24:25] offset:384
	global_load_dwordx2 v[148:149], v184, s[24:25] offset:1024
	global_load_dwordx2 v[150:151], v184, s[24:25] offset:1152
	global_load_dwordx2 v[152:153], v184, s[24:25] offset:1280
	global_load_dwordx2 v[154:155], v184, s[24:25] offset:1408
	v_lshlrev_b64 v[156:157], 11, v[160:161]
	v_lshl_add_u64 v[156:157], v[156:157], 0, v[158:159]
	v_lshlrev_b64 v[156:157], 2, v[156:157]
	v_lshl_add_u64 v[156:157], s[14:15], 0, v[156:157]
	s_mov_b32 s26, 0x3fb504f3
	s_mov_b32 s27, 0xba000000
	s_waitcnt lgkmcnt(0)
	v_lshl_add_u64 v[180:181], v[212:213], 2, v[236:237]
	v_lshl_add_u64 v[210:211], v[212:213], 2, v[238:239]
	global_load_dwordx4 v[166:169], v[178:179], off
	global_load_dwordx4 v[170:173], v[180:181], off
	global_load_dwordx4 v[174:177], v[210:211], off
	v_mov_b64_e32 v[182:183], v[156:157]
	s_mov_b64 s[24:25], 0x20000
	global_load_dwordx4 v[194:197], v[182:183], off
	v_lshl_add_u64 v[182:183], v[182:183], 0, s[24:25]
	global_load_dwordx4 v[198:201], v[182:183], off
	v_lshl_add_u64 v[182:183], v[182:183], 0, s[24:25]
	global_load_dwordx4 v[202:205], v[182:183], off
	v_lshl_add_u64 v[182:183], v[182:183], 0, s[24:25]
	global_load_dwordx4 v[206:209], v[182:183], off
	s_waitcnt vmcnt(0)
	v_pk_add_f32 v[166:167], v[166:167], 1.0 op_sel_hi:[1,0]
	v_pk_add_f32 v[168:169], v[168:169], 1.0 op_sel_hi:[1,0]
	v_mov_b64_e32 v[184:185], v[156:157]
	s_mov_b64 s[24:25], 0x20000
	v_pk_fma_f32 v[194:195], v[140:141], s[26:27], v[194:195] op_sel:[0,1,0] op_sel_hi:[0,1,1]
	v_pk_mul_f32 v[194:195], v[194:195], v[140:141] op_sel:[0,1] op_sel_hi:[1,1]
	v_pk_fma_f32 v[194:195], v[170:171], v[194:195], v[174:175]
	v_pk_mul_f32 v[194:195], v[194:195], s[26:27] op_sel_hi:[1,0]
	v_pk_fma_f32 v[126:127], v[126:127], v[166:167], v[194:195]
	v_pk_fma_f32 v[196:197], v[140:141], s[26:27], v[196:197] op_sel:[0,1,0] op_sel_hi:[0,1,1]
	v_pk_mul_f32 v[196:197], v[196:197], v[140:141] op_sel:[0,1] op_sel_hi:[1,1]
	v_pk_fma_f32 v[196:197], v[172:173], v[196:197], v[176:177]
	v_pk_mul_f32 v[196:197], v[196:197], s[26:27] op_sel_hi:[1,0]
	v_pk_fma_f32 v[128:129], v[128:129], v[168:169], v[196:197]
	global_store_dwordx4 v[184:185], v[126:129], off
	v_lshl_add_u64 v[184:185], v[184:185], 0, s[24:25]
	v_pk_fma_f32 v[198:199], v[142:143], s[26:27], v[198:199] op_sel:[0,1,0] op_sel_hi:[0,1,1]
	v_pk_mul_f32 v[198:199], v[198:199], v[142:143] op_sel:[0,1] op_sel_hi:[1,1]
	v_pk_fma_f32 v[198:199], v[170:171], v[198:199], v[174:175]
	v_pk_mul_f32 v[198:199], v[198:199], s[26:27] op_sel_hi:[1,0]
	v_pk_fma_f32 v[110:111], v[110:111], v[166:167], v[198:199]
	v_pk_fma_f32 v[200:201], v[142:143], s[26:27], v[200:201] op_sel:[0,1,0] op_sel_hi:[0,1,1]
	v_pk_mul_f32 v[200:201], v[200:201], v[142:143] op_sel:[0,1] op_sel_hi:[1,1]
	v_pk_fma_f32 v[200:201], v[172:173], v[200:201], v[176:177]
	v_pk_mul_f32 v[200:201], v[200:201], s[26:27] op_sel_hi:[1,0]
	v_pk_fma_f32 v[112:113], v[112:113], v[168:169], v[200:201]
	global_store_dwordx4 v[184:185], v[110:113], off
	v_lshl_add_u64 v[184:185], v[184:185], 0, s[24:25]
	v_pk_fma_f32 v[202:203], v[144:145], s[26:27], v[202:203] op_sel:[0,1,0] op_sel_hi:[0,1,1]
	v_pk_mul_f32 v[202:203], v[202:203], v[144:145] op_sel:[0,1] op_sel_hi:[1,1]
	v_pk_fma_f32 v[202:203], v[170:171], v[202:203], v[174:175]
	v_pk_mul_f32 v[202:203], v[202:203], s[26:27] op_sel_hi:[1,0]
	v_pk_fma_f32 v[94:95], v[94:95], v[166:167], v[202:203]
	v_pk_fma_f32 v[204:205], v[144:145], s[26:27], v[204:205] op_sel:[0,1,0] op_sel_hi:[0,1,1]
	v_pk_mul_f32 v[204:205], v[204:205], v[144:145] op_sel:[0,1] op_sel_hi:[1,1]
	v_pk_fma_f32 v[204:205], v[172:173], v[204:205], v[176:177]
	v_pk_mul_f32 v[204:205], v[204:205], s[26:27] op_sel_hi:[1,0]
	v_pk_fma_f32 v[96:97], v[96:97], v[168:169], v[204:205]
	global_store_dwordx4 v[184:185], v[94:97], off
	v_lshl_add_u64 v[184:185], v[184:185], 0, s[24:25]
	v_pk_fma_f32 v[206:207], v[146:147], s[26:27], v[206:207] op_sel:[0,1,0] op_sel_hi:[0,1,1]
	v_pk_mul_f32 v[206:207], v[206:207], v[146:147] op_sel:[0,1] op_sel_hi:[1,1]
	v_pk_fma_f32 v[206:207], v[170:171], v[206:207], v[174:175]
	v_pk_mul_f32 v[206:207], v[206:207], s[26:27] op_sel_hi:[1,0]
	v_pk_fma_f32 v[78:79], v[78:79], v[166:167], v[206:207]
	v_pk_fma_f32 v[208:209], v[146:147], s[26:27], v[208:209] op_sel:[0,1,0] op_sel_hi:[0,1,1]
	v_pk_mul_f32 v[208:209], v[208:209], v[146:147] op_sel:[0,1] op_sel_hi:[1,1]
	v_pk_fma_f32 v[208:209], v[172:173], v[208:209], v[176:177]
	v_pk_mul_f32 v[208:209], v[208:209], s[26:27] op_sel_hi:[1,0]
	v_pk_fma_f32 v[80:81], v[80:81], v[168:169], v[208:209]
	global_store_dwordx4 v[184:185], v[78:81], off
	s_mov_b64 s[24:25], 0x100000
	v_lshl_add_u64 v[182:183], v[156:157], 0, s[24:25]
	s_mov_b64 s[24:25], 0x20000
	global_load_dwordx4 v[194:197], v[182:183], off
	v_lshl_add_u64 v[182:183], v[182:183], 0, s[24:25]
	global_load_dwordx4 v[198:201], v[182:183], off
	v_lshl_add_u64 v[182:183], v[182:183], 0, s[24:25]
	global_load_dwordx4 v[202:205], v[182:183], off
	v_lshl_add_u64 v[182:183], v[182:183], 0, s[24:25]
	global_load_dwordx4 v[206:209], v[182:183], off
	s_waitcnt vmcnt(0)
;     __device__ __forceinline__ void operator()(const f32x4 (&acc)[2][2][4][2], const Unit& u, int wr, int wc, int fr, int fq) const {
;     ...
;             for (int m = 0; m < 4; ++m) { const size_t off = (size_t)(row0 + ai * HALF + m * 16) * ldc + col0;
; #pragma unroll
;                 for (int bj = 0; bj < 2; ++bj)
; #pragma unroll
;                     for (int n = 0; n < 2; ++n) { const f32x4 xr = *(const f32x4*)(xres + off + bj * HALF + n * 16);
;                         *(f32x4*)(z + off + bj * HALF + n * 16) = xr * alpha + gv[bj][n] * acc[ai][bj][m][n]; }
;                 if (m == 3) asm volatile("" ::: "memory"); }
;     }
; __device__ __forceinline__ void phase_ln(const float* z, float* xo, const float* __restrict__ g, const float* __restrict__ b, const float* __restrict__ sc, const float* __restrict__ sh, bf16_t* __restrict__ u) {
;     ...
;                 const f32x4 o = (v[k][j] - mean[k]) * rstd[k] * gg + bb;
	s_mov_b64 s[24:25], 0x100000
	v_lshl_add_u64 v[184:185], v[156:157], 0, s[24:25]
	s_mov_b64 s[24:25], 0x20000
	v_pk_fma_f32 v[194:195], v[148:149], s[26:27], v[194:195] op_sel:[0,1,0] op_sel_hi:[0,1,1]
	v_pk_mul_f32 v[194:195], v[194:195], v[148:149] op_sel:[0,1] op_sel_hi:[1,1]
	v_pk_fma_f32 v[194:195], v[170:171], v[194:195], v[174:175]
	v_pk_mul_f32 v[194:195], v[194:195], s[26:27] op_sel_hi:[1,0]
	v_pk_fma_f32 v[62:63], v[62:63], v[166:167], v[194:195]
	v_pk_fma_f32 v[196:197], v[148:149], s[26:27], v[196:197] op_sel:[0,1,0] op_sel_hi:[0,1,1]
	v_pk_mul_f32 v[196:197], v[196:197], v[148:149] op_sel:[0,1] op_sel_hi:[1,1]
	v_pk_fma_f32 v[196:197], v[172:173], v[196:197], v[176:177]
	v_pk_mul_f32 v[196:197], v[196:197], s[26:27] op_sel_hi:[1,0]
	v_pk_fma_f32 v[64:65], v[64:65], v[168:169], v[196:197]
	global_store_dwordx4 v[184:185], v[62:65], off
	v_lshl_add_u64 v[184:185], v[184:185], 0, s[24:25]
	v_pk_fma_f32 v[198:199], v[150:151], s[26:27], v[198:199] op_sel:[0,1,0] op_sel_hi:[0,1,1]
	v_pk_mul_f32 v[198:199], v[198:199], v[150:151] op_sel:[0,1] op_sel_hi:[1,1]
	v_pk_fma_f32 v[198:199], v[170:171], v[198:199], v[174:175]
	v_pk_mul_f32 v[198:199], v[198:199], s[26:27] op_sel_hi:[1,0]
	v_pk_fma_f32 v[46:47], v[46:47], v[166:167], v[198:199]
	v_pk_fma_f32 v[200:201], v[150:151], s[26:27], v[200:201] op_sel:[0,1,0] op_sel_hi:[0,1,1]
	v_pk_mul_f32 v[200:201], v[200:201], v[150:151] op_sel:[0,1] op_sel_hi:[1,1]
	v_pk_fma_f32 v[200:201], v[172:173], v[200:201], v[176:177]
	v_pk_mul_f32 v[200:201], v[200:201], s[26:27] op_sel_hi:[1,0]
	v_pk_fma_f32 v[48:49], v[48:49], v[168:169], v[200:201]
	global_store_dwordx4 v[184:185], v[46:49], off
	v_lshl_add_u64 v[184:185], v[184:185], 0, s[24:25]
	v_pk_fma_f32 v[202:203], v[152:153], s[26:27], v[202:203] op_sel:[0,1,0] op_sel_hi:[0,1,1]
	v_pk_mul_f32 v[202:203], v[202:203], v[152:153] op_sel:[0,1] op_sel_hi:[1,1]
	v_pk_fma_f32 v[202:203], v[170:171], v[202:203], v[174:175]
	v_pk_mul_f32 v[202:203], v[202:203], s[26:27] op_sel_hi:[1,0]
	v_pk_fma_f32 v[30:31], v[30:31], v[166:167], v[202:203]
	v_pk_fma_f32 v[204:205], v[152:153], s[26:27], v[204:205] op_sel:[0,1,0] op_sel_hi:[0,1,1]
	v_pk_mul_f32 v[204:205], v[204:205], v[152:153] op_sel:[0,1] op_sel_hi:[1,1]
	v_pk_fma_f32 v[204:205], v[172:173], v[204:205], v[176:177]
	v_pk_mul_f32 v[204:205], v[204:205], s[26:27] op_sel_hi:[1,0]
	v_pk_fma_f32 v[32:33], v[32:33], v[168:169], v[204:205]
	global_store_dwordx4 v[184:185], v[30:33], off
	v_lshl_add_u64 v[184:185], v[184:185], 0, s[24:25]
	v_pk_fma_f32 v[206:207], v[154:155], s[26:27], v[206:207] op_sel:[0,1,0] op_sel_hi:[0,1,1]
	v_pk_mul_f32 v[206:207], v[206:207], v[154:155] op_sel:[0,1] op_sel_hi:[1,1]
	v_pk_fma_f32 v[206:207], v[170:171], v[206:207], v[174:175]
	v_pk_mul_f32 v[206:207], v[206:207], s[26:27] op_sel_hi:[1,0]
	v_pk_fma_f32 v[14:15], v[14:15], v[166:167], v[206:207]
	v_pk_fma_f32 v[208:209], v[154:155], s[26:27], v[208:209] op_sel:[0,1,0] op_sel_hi:[0,1,1]
	v_pk_mul_f32 v[208:209], v[208:209], v[154:155] op_sel:[0,1] op_sel_hi:[1,1]
	v_pk_fma_f32 v[208:209], v[172:173], v[208:209], v[176:177]
	v_pk_mul_f32 v[208:209], v[208:209], s[26:27] op_sel_hi:[1,0]
	v_pk_fma_f32 v[16:17], v[16:17], v[168:169], v[208:209]
	global_store_dwordx4 v[184:185], v[14:17], off
	global_load_dwordx4 v[166:169], v[178:179], off offset:64
	global_load_dwordx4 v[170:173], v[180:181], off offset:64
	global_load_dwordx4 v[174:177], v[210:211], off offset:64
	v_mov_b64_e32 v[182:183], v[156:157]
	s_mov_b64 s[24:25], 0x20000
	global_load_dwordx4 v[194:197], v[182:183], off offset:64
	v_lshl_add_u64 v[182:183], v[182:183], 0, s[24:25]
	global_load_dwordx4 v[198:201], v[182:183], off offset:64
	v_lshl_add_u64 v[182:183], v[182:183], 0, s[24:25]
	global_load_dwordx4 v[202:205], v[182:183], off offset:64
	v_lshl_add_u64 v[182:183], v[182:183], 0, s[24:25]
	global_load_dwordx4 v[206:209], v[182:183], off offset:64
	s_mov_b64 s[24:25], 0x100000
	v_lshl_add_u64 v[182:183], v[156:157], 0, s[24:25]
	s_mov_b64 s[24:25], 0x20000
	global_load_dwordx4 v[126:129], v[182:183], off offset:64
	v_lshl_add_u64 v[182:183], v[182:183], 0, s[24:25]
	global_load_dwordx4 v[110:113], v[182:183], off offset:64
	v_lshl_add_u64 v[182:183], v[182:183], 0, s[24:25]
	global_load_dwordx4 v[94:97], v[182:183], off offset:64
	v_lshl_add_u64 v[182:183], v[182:183], 0, s[24:25]
	global_load_dwordx4 v[78:81], v[182:183], off offset:64
	s_waitcnt vmcnt(0)
;     __device__ __forceinline__ void operator()(const f32x4 (&acc)[2][2][4][2], const Unit& u, int wr, int wc, int fr, int fq) const {
;     ...
;             for (int m = 0; m < 4; ++m) { const size_t off = (size_t)(row0 + ai * HALF + m * 16) * ldc + col0;
; #pragma unroll
;                 for (int bj = 0; bj < 2; ++bj)
; #pragma unroll
;                     for (int n = 0; n < 2; ++n) { const f32x4 xr = *(const f32x4*)(xres + off + bj * HALF + n * 16);
;                         *(f32x4*)(z + off + bj * HALF + n * 16) = xr * alpha + gv[bj][n] * acc[ai][bj][m][n]; }
;                 if (m == 3) asm volatile("" ::: "memory"); }
;     }
; __device__ __forceinline__ void phase_ln(const float* z, float* xo, const float* __restrict__ g, const float* __restrict__ b, const float* __restrict__ sc, const float* __restrict__ sh, bf16_t* __restrict__ u) {
;     ...
;                 const f32x4 o = (v[k][j] - mean[k]) * rstd[k] * gg + bb;
	v_pk_add_f32 v[166:167], v[166:167], 1.0 op_sel_hi:[1,0]
	v_pk_add_f32 v[168:169], v[168:169], 1.0 op_sel_hi:[1,0]
	v_mov_b64_e32 v[184:185], v[156:157]
	s_mov_b64 s[24:25], 0x20000
	v_pk_fma_f32 v[194:195], v[140:141], s[26:27], v[194:195] op_sel:[0,1,0] op_sel_hi:[0,1,1]
	v_pk_mul_f32 v[194:195], v[194:195], v[140:141] op_sel:[0,1] op_sel_hi:[1,1]
	v_pk_fma_f32 v[194:195], v[170:171], v[194:195], v[174:175]
	v_pk_mul_f32 v[194:195], v[194:195], s[26:27] op_sel_hi:[1,0]
	v_pk_fma_f32 v[122:123], v[122:123], v[166:167], v[194:195]
	v_pk_fma_f32 v[196:197], v[140:141], s[26:27], v[196:197] op_sel:[0,1,0] op_sel_hi:[0,1,1]
	v_pk_mul_f32 v[196:197], v[196:197], v[140:141] op_sel:[0,1] op_sel_hi:[1,1]
	v_pk_fma_f32 v[196:197], v[172:173], v[196:197], v[176:177]
	v_pk_mul_f32 v[196:197], v[196:197], s[26:27] op_sel_hi:[1,0]
	v_pk_fma_f32 v[124:125], v[124:125], v[168:169], v[196:197]
	global_store_dwordx4 v[184:185], v[122:125], off offset:64
	v_lshl_add_u64 v[184:185], v[184:185], 0, s[24:25]
	v_pk_fma_f32 v[198:199], v[142:143], s[26:27], v[198:199] op_sel:[0,1,0] op_sel_hi:[0,1,1]
	v_pk_mul_f32 v[198:199], v[198:199], v[142:143] op_sel:[0,1] op_sel_hi:[1,1]
	v_pk_fma_f32 v[198:199], v[170:171], v[198:199], v[174:175]
	v_pk_mul_f32 v[198:199], v[198:199], s[26:27] op_sel_hi:[1,0]
	v_pk_fma_f32 v[106:107], v[106:107], v[166:167], v[198:199]
	v_pk_fma_f32 v[200:201], v[142:143], s[26:27], v[200:201] op_sel:[0,1,0] op_sel_hi:[0,1,1]
	v_pk_mul_f32 v[200:201], v[200:201], v[142:143] op_sel:[0,1] op_sel_hi:[1,1]
	v_pk_fma_f32 v[200:201], v[172:173], v[200:201], v[176:177]
	v_pk_mul_f32 v[200:201], v[200:201], s[26:27] op_sel_hi:[1,0]
	v_pk_fma_f32 v[108:109], v[108:109], v[168:169], v[200:201]
	global_store_dwordx4 v[184:185], v[106:109], off offset:64
	v_lshl_add_u64 v[184:185], v[184:185], 0, s[24:25]
	v_pk_fma_f32 v[202:203], v[144:145], s[26:27], v[202:203] op_sel:[0,1,0] op_sel_hi:[0,1,1]
	v_pk_mul_f32 v[202:203], v[202:203], v[144:145] op_sel:[0,1] op_sel_hi:[1,1]
	v_pk_fma_f32 v[202:203], v[170:171], v[202:203], v[174:175]
	v_pk_mul_f32 v[202:203], v[202:203], s[26:27] op_sel_hi:[1,0]
	v_pk_fma_f32 v[90:91], v[90:91], v[166:167], v[202:203]
	v_pk_fma_f32 v[204:205], v[144:145], s[26:27], v[204:205] op_sel:[0,1,0] op_sel_hi:[0,1,1]
	v_pk_mul_f32 v[204:205], v[204:205], v[144:145] op_sel:[0,1] op_sel_hi:[1,1]
	v_pk_fma_f32 v[204:205], v[172:173], v[204:205], v[176:177]
	v_pk_mul_f32 v[204:205], v[204:205], s[26:27] op_sel_hi:[1,0]
	v_pk_fma_f32 v[92:93], v[92:93], v[168:169], v[204:205]
	global_store_dwordx4 v[184:185], v[90:93], off offset:64
	v_lshl_add_u64 v[184:185], v[184:185], 0, s[24:25]
	v_pk_fma_f32 v[206:207], v[146:147], s[26:27], v[206:207] op_sel:[0,1,0] op_sel_hi:[0,1,1]
	v_pk_mul_f32 v[206:207], v[206:207], v[146:147] op_sel:[0,1] op_sel_hi:[1,1]
	v_pk_fma_f32 v[206:207], v[170:171], v[206:207], v[174:175]
	v_pk_mul_f32 v[206:207], v[206:207], s[26:27] op_sel_hi:[1,0]
	v_pk_fma_f32 v[74:75], v[74:75], v[166:167], v[206:207]
	v_pk_fma_f32 v[208:209], v[146:147], s[26:27], v[208:209] op_sel:[0,1,0] op_sel_hi:[0,1,1]
	v_pk_mul_f32 v[208:209], v[208:209], v[146:147] op_sel:[0,1] op_sel_hi:[1,1]
	v_pk_fma_f32 v[208:209], v[172:173], v[208:209], v[176:177]
	v_pk_mul_f32 v[208:209], v[208:209], s[26:27] op_sel_hi:[1,0]
	v_pk_fma_f32 v[76:77], v[76:77], v[168:169], v[208:209]
	global_store_dwordx4 v[184:185], v[74:77], off offset:64
	s_mov_b64 s[24:25], 0x100000
	v_lshl_add_u64 v[184:185], v[156:157], 0, s[24:25]
	s_mov_b64 s[24:25], 0x20000
	v_pk_fma_f32 v[126:127], v[148:149], s[26:27], v[126:127] op_sel:[0,1,0] op_sel_hi:[0,1,1]
	v_pk_mul_f32 v[126:127], v[126:127], v[148:149] op_sel:[0,1] op_sel_hi:[1,1]
	v_pk_fma_f32 v[126:127], v[170:171], v[126:127], v[174:175]
	v_pk_mul_f32 v[126:127], v[126:127], s[26:27] op_sel_hi:[1,0]
	v_pk_fma_f32 v[58:59], v[58:59], v[166:167], v[126:127]
	v_pk_fma_f32 v[128:129], v[148:149], s[26:27], v[128:129] op_sel:[0,1,0] op_sel_hi:[0,1,1]
	v_pk_mul_f32 v[128:129], v[128:129], v[148:149] op_sel:[0,1] op_sel_hi:[1,1]
	v_pk_fma_f32 v[128:129], v[172:173], v[128:129], v[176:177]
	v_pk_mul_f32 v[128:129], v[128:129], s[26:27] op_sel_hi:[1,0]
	v_pk_fma_f32 v[60:61], v[60:61], v[168:169], v[128:129]
	global_store_dwordx4 v[184:185], v[58:61], off offset:64
	v_lshl_add_u64 v[184:185], v[184:185], 0, s[24:25]
	v_pk_fma_f32 v[110:111], v[150:151], s[26:27], v[110:111] op_sel:[0,1,0] op_sel_hi:[0,1,1]
	v_pk_mul_f32 v[110:111], v[110:111], v[150:151] op_sel:[0,1] op_sel_hi:[1,1]
	v_pk_fma_f32 v[110:111], v[170:171], v[110:111], v[174:175]
	v_pk_mul_f32 v[110:111], v[110:111], s[26:27] op_sel_hi:[1,0]
	v_pk_fma_f32 v[42:43], v[42:43], v[166:167], v[110:111]
	v_pk_fma_f32 v[112:113], v[150:151], s[26:27], v[112:113] op_sel:[0,1,0] op_sel_hi:[0,1,1]
	v_pk_mul_f32 v[112:113], v[112:113], v[150:151] op_sel:[0,1] op_sel_hi:[1,1]
	v_pk_fma_f32 v[112:113], v[172:173], v[112:113], v[176:177]
	v_pk_mul_f32 v[112:113], v[112:113], s[26:27] op_sel_hi:[1,0]
	v_pk_fma_f32 v[44:45], v[44:45], v[168:169], v[112:113]
	global_store_dwordx4 v[184:185], v[42:45], off offset:64
	v_lshl_add_u64 v[184:185], v[184:185], 0, s[24:25]
	v_pk_fma_f32 v[94:95], v[152:153], s[26:27], v[94:95] op_sel:[0,1,0] op_sel_hi:[0,1,1]
	v_pk_mul_f32 v[94:95], v[94:95], v[152:153] op_sel:[0,1] op_sel_hi:[1,1]
	v_pk_fma_f32 v[94:95], v[170:171], v[94:95], v[174:175]
	v_pk_mul_f32 v[94:95], v[94:95], s[26:27] op_sel_hi:[1,0]
	v_pk_fma_f32 v[26:27], v[26:27], v[166:167], v[94:95]
	v_pk_fma_f32 v[96:97], v[152:153], s[26:27], v[96:97] op_sel:[0,1,0] op_sel_hi:[0,1,1]
	v_pk_mul_f32 v[96:97], v[96:97], v[152:153] op_sel:[0,1] op_sel_hi:[1,1]
;     __device__ __forceinline__ void operator()(const f32x4 (&acc)[2][2][4][2], const Unit& u, int wr, int wc, int fr, int fq) const {
;     ...
;             for (int m = 0; m < 4; ++m) { const size_t off = (size_t)(row0 + ai * HALF + m * 16) * ldc + col0;
; #pragma unroll
;                 for (int bj = 0; bj < 2; ++bj)
; #pragma unroll
;                     for (int n = 0; n < 2; ++n) { const f32x4 xr = *(const f32x4*)(xres + off + bj * HALF + n * 16);
;                         *(f32x4*)(z + off + bj * HALF + n * 16) = xr * alpha + gv[bj][n] * acc[ai][bj][m][n]; }
;                 if (m == 3) asm volatile("" ::: "memory"); }
;     }
; __device__ __forceinline__ void phase_ln(const float* z, float* xo, const float* __restrict__ g, const float* __restrict__ b, const float* __restrict__ sc, const float* __restrict__ sh, bf16_t* __restrict__ u) {
;     ...
;                 const f32x4 o = (v[k][j] - mean[k]) * rstd[k] * gg + bb;
	v_pk_fma_f32 v[96:97], v[172:173], v[96:97], v[176:177]
	v_pk_mul_f32 v[96:97], v[96:97], s[26:27] op_sel_hi:[1,0]
	v_pk_fma_f32 v[28:29], v[28:29], v[168:169], v[96:97]
	global_store_dwordx4 v[184:185], v[26:29], off offset:64
	v_lshl_add_u64 v[184:185], v[184:185], 0, s[24:25]
	v_pk_fma_f32 v[78:79], v[154:155], s[26:27], v[78:79] op_sel:[0,1,0] op_sel_hi:[0,1,1]
	v_pk_mul_f32 v[78:79], v[78:79], v[154:155] op_sel:[0,1] op_sel_hi:[1,1]
	v_pk_fma_f32 v[78:79], v[170:171], v[78:79], v[174:175]
	v_pk_mul_f32 v[78:79], v[78:79], s[26:27] op_sel_hi:[1,0]
	v_pk_fma_f32 v[10:11], v[10:11], v[166:167], v[78:79]
	v_pk_fma_f32 v[80:81], v[154:155], s[26:27], v[80:81] op_sel:[0,1,0] op_sel_hi:[0,1,1]
	v_pk_mul_f32 v[80:81], v[80:81], v[154:155] op_sel:[0,1] op_sel_hi:[1,1]
	v_pk_fma_f32 v[80:81], v[172:173], v[80:81], v[176:177]
	v_pk_mul_f32 v[80:81], v[80:81], s[26:27] op_sel_hi:[1,0]
	v_pk_fma_f32 v[12:13], v[12:13], v[168:169], v[80:81]
	global_store_dwordx4 v[184:185], v[10:13], off offset:64
	global_load_dwordx4 v[166:169], v[178:179], off offset:512
	global_load_dwordx4 v[170:173], v[180:181], off offset:512
	global_load_dwordx4 v[174:177], v[210:211], off offset:512
	v_mov_b64_e32 v[182:183], v[156:157]
	s_mov_b64 s[24:25], 0x20000
	global_load_dwordx4 v[194:197], v[182:183], off offset:512
	v_lshl_add_u64 v[182:183], v[182:183], 0, s[24:25]
	global_load_dwordx4 v[198:201], v[182:183], off offset:512
	v_lshl_add_u64 v[182:183], v[182:183], 0, s[24:25]
	global_load_dwordx4 v[202:205], v[182:183], off offset:512
	v_lshl_add_u64 v[182:183], v[182:183], 0, s[24:25]
	global_load_dwordx4 v[206:209], v[182:183], off offset:512
	s_mov_b64 s[24:25], 0x100000
	v_lshl_add_u64 v[182:183], v[156:157], 0, s[24:25]
	s_mov_b64 s[24:25], 0x20000
	global_load_dwordx4 v[126:129], v[182:183], off offset:512
	v_lshl_add_u64 v[182:183], v[182:183], 0, s[24:25]
	global_load_dwordx4 v[110:113], v[182:183], off offset:512
	v_lshl_add_u64 v[182:183], v[182:183], 0, s[24:25]
	global_load_dwordx4 v[94:97], v[182:183], off offset:512
	v_lshl_add_u64 v[182:183], v[182:183], 0, s[24:25]
	global_load_dwordx4 v[78:81], v[182:183], off offset:512
	s_waitcnt vmcnt(0)
	v_pk_add_f32 v[166:167], v[166:167], 1.0 op_sel_hi:[1,0]
	v_pk_add_f32 v[168:169], v[168:169], 1.0 op_sel_hi:[1,0]
	v_mov_b64_e32 v[184:185], v[156:157]
	s_mov_b64 s[24:25], 0x20000
	v_pk_fma_f32 v[194:195], v[140:141], s[26:27], v[194:195] op_sel:[0,1,0] op_sel_hi:[0,1,1]
	v_pk_mul_f32 v[194:195], v[194:195], v[140:141] op_sel:[0,1] op_sel_hi:[1,1]
	v_pk_fma_f32 v[194:195], v[170:171], v[194:195], v[174:175]
	v_pk_mul_f32 v[194:195], v[194:195], s[26:27] op_sel_hi:[1,0]
	v_pk_fma_f32 v[118:119], v[118:119], v[166:167], v[194:195]
	v_pk_fma_f32 v[196:197], v[140:141], s[26:27], v[196:197] op_sel:[0,1,0] op_sel_hi:[0,1,1]
	v_pk_mul_f32 v[196:197], v[196:197], v[140:141] op_sel:[0,1] op_sel_hi:[1,1]
	v_pk_fma_f32 v[196:197], v[172:173], v[196:197], v[176:177]
	v_pk_mul_f32 v[196:197], v[196:197], s[26:27] op_sel_hi:[1,0]
	v_pk_fma_f32 v[120:121], v[120:121], v[168:169], v[196:197]
	global_store_dwordx4 v[184:185], v[118:121], off offset:512
	v_lshl_add_u64 v[184:185], v[184:185], 0, s[24:25]
	v_pk_fma_f32 v[198:199], v[142:143], s[26:27], v[198:199] op_sel:[0,1,0] op_sel_hi:[0,1,1]
	v_pk_mul_f32 v[198:199], v[198:199], v[142:143] op_sel:[0,1] op_sel_hi:[1,1]
	v_pk_fma_f32 v[198:199], v[170:171], v[198:199], v[174:175]
	v_pk_mul_f32 v[198:199], v[198:199], s[26:27] op_sel_hi:[1,0]
	v_pk_fma_f32 v[102:103], v[102:103], v[166:167], v[198:199]
	v_pk_fma_f32 v[200:201], v[142:143], s[26:27], v[200:201] op_sel:[0,1,0] op_sel_hi:[0,1,1]
	v_pk_mul_f32 v[200:201], v[200:201], v[142:143] op_sel:[0,1] op_sel_hi:[1,1]
	v_pk_fma_f32 v[200:201], v[172:173], v[200:201], v[176:177]
	v_pk_mul_f32 v[200:201], v[200:201], s[26:27] op_sel_hi:[1,0]
	v_pk_fma_f32 v[104:105], v[104:105], v[168:169], v[200:201]
	global_store_dwordx4 v[184:185], v[102:105], off offset:512
	v_lshl_add_u64 v[184:185], v[184:185], 0, s[24:25]
	v_pk_fma_f32 v[202:203], v[144:145], s[26:27], v[202:203] op_sel:[0,1,0] op_sel_hi:[0,1,1]
	v_pk_mul_f32 v[202:203], v[202:203], v[144:145] op_sel:[0,1] op_sel_hi:[1,1]
	v_pk_fma_f32 v[202:203], v[170:171], v[202:203], v[174:175]
	v_pk_mul_f32 v[202:203], v[202:203], s[26:27] op_sel_hi:[1,0]
	v_pk_fma_f32 v[86:87], v[86:87], v[166:167], v[202:203]
	v_pk_fma_f32 v[204:205], v[144:145], s[26:27], v[204:205] op_sel:[0,1,0] op_sel_hi:[0,1,1]
	v_pk_mul_f32 v[204:205], v[204:205], v[144:145] op_sel:[0,1] op_sel_hi:[1,1]
	v_pk_fma_f32 v[204:205], v[172:173], v[204:205], v[176:177]
	v_pk_mul_f32 v[204:205], v[204:205], s[26:27] op_sel_hi:[1,0]
	v_pk_fma_f32 v[88:89], v[88:89], v[168:169], v[204:205]
	global_store_dwordx4 v[184:185], v[86:89], off offset:512
	v_lshl_add_u64 v[184:185], v[184:185], 0, s[24:25]
	v_pk_fma_f32 v[206:207], v[146:147], s[26:27], v[206:207] op_sel:[0,1,0] op_sel_hi:[0,1,1]
	v_pk_mul_f32 v[206:207], v[206:207], v[146:147] op_sel:[0,1] op_sel_hi:[1,1]
	v_pk_fma_f32 v[206:207], v[170:171], v[206:207], v[174:175]
	v_pk_mul_f32 v[206:207], v[206:207], s[26:27] op_sel_hi:[1,0]
	v_pk_fma_f32 v[70:71], v[70:71], v[166:167], v[206:207]
	v_pk_fma_f32 v[208:209], v[146:147], s[26:27], v[208:209] op_sel:[0,1,0] op_sel_hi:[0,1,1]
	v_pk_mul_f32 v[208:209], v[208:209], v[146:147] op_sel:[0,1] op_sel_hi:[1,1]
	v_pk_fma_f32 v[208:209], v[172:173], v[208:209], v[176:177]
	v_pk_mul_f32 v[208:209], v[208:209], s[26:27] op_sel_hi:[1,0]
	v_pk_fma_f32 v[72:73], v[72:73], v[168:169], v[208:209]
	global_store_dwordx4 v[184:185], v[70:73], off offset:512
	s_mov_b64 s[24:25], 0x100000
	v_lshl_add_u64 v[184:185], v[156:157], 0, s[24:25]
;     __device__ __forceinline__ void operator()(const f32x4 (&acc)[2][2][4][2], const Unit& u, int wr, int wc, int fr, int fq) const {
;     ...
;             for (int m = 0; m < 4; ++m) { const size_t off = (size_t)(row0 + ai * HALF + m * 16) * ldc + col0;
; #pragma unroll
;                 for (int bj = 0; bj < 2; ++bj)
; #pragma unroll
;                     for (int n = 0; n < 2; ++n) { const f32x4 xr = *(const f32x4*)(xres + off + bj * HALF + n * 16);
;                         *(f32x4*)(z + off + bj * HALF + n * 16) = xr * alpha + gv[bj][n] * acc[ai][bj][m][n]; }
;                 if (m == 3) asm volatile("" ::: "memory"); }
;     }
; __device__ __forceinline__ void phase_ln(const float* z, float* xo, const float* __restrict__ g, const float* __restrict__ b, const float* __restrict__ sc, const float* __restrict__ sh, bf16_t* __restrict__ u) {
;     ...
;                 const f32x4 o = (v[k][j] - mean[k]) * rstd[k] * gg + bb;
	s_mov_b64 s[24:25], 0x20000
	v_pk_fma_f32 v[126:127], v[148:149], s[26:27], v[126:127] op_sel:[0,1,0] op_sel_hi:[0,1,1]
	v_pk_mul_f32 v[126:127], v[126:127], v[148:149] op_sel:[0,1] op_sel_hi:[1,1]
	v_pk_fma_f32 v[126:127], v[170:171], v[126:127], v[174:175]
	v_pk_mul_f32 v[126:127], v[126:127], s[26:27] op_sel_hi:[1,0]
	v_pk_fma_f32 v[54:55], v[54:55], v[166:167], v[126:127]
	v_pk_fma_f32 v[128:129], v[148:149], s[26:27], v[128:129] op_sel:[0,1,0] op_sel_hi:[0,1,1]
	v_pk_mul_f32 v[128:129], v[128:129], v[148:149] op_sel:[0,1] op_sel_hi:[1,1]
	v_pk_fma_f32 v[128:129], v[172:173], v[128:129], v[176:177]
	v_pk_mul_f32 v[128:129], v[128:129], s[26:27] op_sel_hi:[1,0]
	v_pk_fma_f32 v[56:57], v[56:57], v[168:169], v[128:129]
	global_store_dwordx4 v[184:185], v[54:57], off offset:512
	v_lshl_add_u64 v[184:185], v[184:185], 0, s[24:25]
	v_pk_fma_f32 v[110:111], v[150:151], s[26:27], v[110:111] op_sel:[0,1,0] op_sel_hi:[0,1,1]
	v_pk_mul_f32 v[110:111], v[110:111], v[150:151] op_sel:[0,1] op_sel_hi:[1,1]
	v_pk_fma_f32 v[110:111], v[170:171], v[110:111], v[174:175]
	v_pk_mul_f32 v[110:111], v[110:111], s[26:27] op_sel_hi:[1,0]
	v_pk_fma_f32 v[38:39], v[38:39], v[166:167], v[110:111]
	v_pk_fma_f32 v[112:113], v[150:151], s[26:27], v[112:113] op_sel:[0,1,0] op_sel_hi:[0,1,1]
	v_pk_mul_f32 v[112:113], v[112:113], v[150:151] op_sel:[0,1] op_sel_hi:[1,1]
	v_pk_fma_f32 v[112:113], v[172:173], v[112:113], v[176:177]
	v_pk_mul_f32 v[112:113], v[112:113], s[26:27] op_sel_hi:[1,0]
	v_pk_fma_f32 v[40:41], v[40:41], v[168:169], v[112:113]
	global_store_dwordx4 v[184:185], v[38:41], off offset:512
	v_lshl_add_u64 v[184:185], v[184:185], 0, s[24:25]
	v_pk_fma_f32 v[94:95], v[152:153], s[26:27], v[94:95] op_sel:[0,1,0] op_sel_hi:[0,1,1]
	v_pk_mul_f32 v[94:95], v[94:95], v[152:153] op_sel:[0,1] op_sel_hi:[1,1]
	v_pk_fma_f32 v[94:95], v[170:171], v[94:95], v[174:175]
	v_pk_mul_f32 v[94:95], v[94:95], s[26:27] op_sel_hi:[1,0]
	v_pk_fma_f32 v[22:23], v[22:23], v[166:167], v[94:95]
	v_pk_fma_f32 v[96:97], v[152:153], s[26:27], v[96:97] op_sel:[0,1,0] op_sel_hi:[0,1,1]
	v_pk_mul_f32 v[96:97], v[96:97], v[152:153] op_sel:[0,1] op_sel_hi:[1,1]
	v_pk_fma_f32 v[96:97], v[172:173], v[96:97], v[176:177]
	v_pk_mul_f32 v[96:97], v[96:97], s[26:27] op_sel_hi:[1,0]
	v_pk_fma_f32 v[24:25], v[24:25], v[168:169], v[96:97]
	global_store_dwordx4 v[184:185], v[22:25], off offset:512
	v_lshl_add_u64 v[184:185], v[184:185], 0, s[24:25]
	v_pk_fma_f32 v[78:79], v[154:155], s[26:27], v[78:79] op_sel:[0,1,0] op_sel_hi:[0,1,1]
	v_pk_mul_f32 v[78:79], v[78:79], v[154:155] op_sel:[0,1] op_sel_hi:[1,1]
	v_pk_fma_f32 v[78:79], v[170:171], v[78:79], v[174:175]
	v_pk_mul_f32 v[78:79], v[78:79], s[26:27] op_sel_hi:[1,0]
	v_pk_fma_f32 v[6:7], v[6:7], v[166:167], v[78:79]
	v_pk_fma_f32 v[80:81], v[154:155], s[26:27], v[80:81] op_sel:[0,1,0] op_sel_hi:[0,1,1]
	v_pk_mul_f32 v[80:81], v[80:81], v[154:155] op_sel:[0,1] op_sel_hi:[1,1]
	v_pk_fma_f32 v[80:81], v[172:173], v[80:81], v[176:177]
	v_pk_mul_f32 v[80:81], v[80:81], s[26:27] op_sel_hi:[1,0]
	v_pk_fma_f32 v[8:9], v[8:9], v[168:169], v[80:81]
	global_store_dwordx4 v[184:185], v[6:9], off offset:512
	global_load_dwordx4 v[166:169], v[178:179], off offset:576
	global_load_dwordx4 v[170:173], v[180:181], off offset:576
	global_load_dwordx4 v[174:177], v[210:211], off offset:576
	v_mov_b64_e32 v[182:183], v[156:157]
	s_mov_b64 s[24:25], 0x20000
	global_load_dwordx4 v[194:197], v[182:183], off offset:576
	v_lshl_add_u64 v[182:183], v[182:183], 0, s[24:25]
	global_load_dwordx4 v[198:201], v[182:183], off offset:576
	v_lshl_add_u64 v[182:183], v[182:183], 0, s[24:25]
	global_load_dwordx4 v[202:205], v[182:183], off offset:576
	v_lshl_add_u64 v[182:183], v[182:183], 0, s[24:25]
	global_load_dwordx4 v[206:209], v[182:183], off offset:576
	s_mov_b64 s[24:25], 0x100000
	v_lshl_add_u64 v[182:183], v[156:157], 0, s[24:25]
	s_mov_b64 s[24:25], 0x20000
	global_load_dwordx4 v[126:129], v[182:183], off offset:576
	v_lshl_add_u64 v[182:183], v[182:183], 0, s[24:25]
	global_load_dwordx4 v[110:113], v[182:183], off offset:576
	v_lshl_add_u64 v[182:183], v[182:183], 0, s[24:25]
	global_load_dwordx4 v[94:97], v[182:183], off offset:576
	v_lshl_add_u64 v[182:183], v[182:183], 0, s[24:25]
	global_load_dwordx4 v[78:81], v[182:183], off offset:576
	s_waitcnt vmcnt(0)
; #define PG8_BAR __builtin_amdgcn_s_barrier()
;     __device__ __forceinline__ void operator()(const f32x4 (&acc)[2][2][4][2], const Unit& u, int wr, int wc, int fr, int fq) const {
;     ...
;             for (int m = 0; m < 4; ++m) { const size_t off = (size_t)(row0 + ai * HALF + m * 16) * ldc + col0;
; #pragma unroll
;                 for (int bj = 0; bj < 2; ++bj)
; #pragma unroll
;                     for (int n = 0; n < 2; ++n) { const f32x4 xr = *(const f32x4*)(xres + off + bj * HALF + n * 16);
;                         *(f32x4*)(z + off + bj * HALF + n * 16) = xr * alpha + gv[bj][n] * acc[ai][bj][m][n]; }
;                 if (m == 3) asm volatile("" ::: "memory"); }
;     }
; template <class Epi, class Sched, bool ALIGN_EPI = false, bool SP2 = false>
; __device__ __forceinline__ void gemm_phase(PG8_LAS unsigned char* lds, const Gemm g, const Sched& S, const Epi& E) {
;     ...
;         if constexpr (ALIGN_EPI) { if (wr == 0) PG8_BAR; }
;         if constexpr (!Epi::AFTER_DRAIN) { E(acc, cur, wr, wc, fr, fq); S.done(cur); }
;         if (!has_next) break;
; #pragma unroll
;         for (int a = 0; a < 2; ++a)
; #pragma unroll
;             for (int b = 0; b < 2; ++b)
; #pragma unroll
;                 for (int m = 0; m < 4; ++m)
; #pragma unroll
;                     for (int n = 0; n < 2; ++n) acc[a][b][m][n] = (f32x4){0.f, 0.f, 0.f, 0.f};
;         cur = nxt; cA = nA; cB = nB; ++ui;
;         if constexpr (ALIGN_EPI) { if (wr == 1) PG8_BAR; }
; __device__ __forceinline__ void phase_ln(const float* z, float* xo, const float* __restrict__ g, const float* __restrict__ b, const float* __restrict__ sc, const float* __restrict__ sh, bf16_t* __restrict__ u) {
;     ...
;                 const f32x4 o = (v[k][j] - mean[k]) * rstd[k] * gg + bb;
	v_pk_add_f32 v[166:167], v[166:167], 1.0 op_sel_hi:[1,0]
	v_pk_add_f32 v[168:169], v[168:169], 1.0 op_sel_hi:[1,0]
	v_mov_b64_e32 v[184:185], v[156:157]
	s_mov_b64 s[24:25], 0x20000
	v_pk_fma_f32 v[194:195], v[140:141], s[26:27], v[194:195] op_sel:[0,1,0] op_sel_hi:[0,1,1]
	v_pk_mul_f32 v[194:195], v[194:195], v[140:141] op_sel:[0,1] op_sel_hi:[1,1]
	v_pk_fma_f32 v[194:195], v[170:171], v[194:195], v[174:175]
	v_pk_mul_f32 v[194:195], v[194:195], s[26:27] op_sel_hi:[1,0]
	v_pk_fma_f32 v[114:115], v[114:115], v[166:167], v[194:195]
	v_pk_fma_f32 v[196:197], v[140:141], s[26:27], v[196:197] op_sel:[0,1,0] op_sel_hi:[0,1,1]
	v_pk_mul_f32 v[196:197], v[196:197], v[140:141] op_sel:[0,1] op_sel_hi:[1,1]
	v_pk_fma_f32 v[196:197], v[172:173], v[196:197], v[176:177]
	v_pk_mul_f32 v[196:197], v[196:197], s[26:27] op_sel_hi:[1,0]
	v_pk_fma_f32 v[116:117], v[116:117], v[168:169], v[196:197]
	global_store_dwordx4 v[184:185], v[114:117], off offset:576
	v_lshl_add_u64 v[184:185], v[184:185], 0, s[24:25]
	v_pk_fma_f32 v[198:199], v[142:143], s[26:27], v[198:199] op_sel:[0,1,0] op_sel_hi:[0,1,1]
	v_pk_mul_f32 v[198:199], v[198:199], v[142:143] op_sel:[0,1] op_sel_hi:[1,1]
	v_pk_fma_f32 v[198:199], v[170:171], v[198:199], v[174:175]
	v_pk_mul_f32 v[198:199], v[198:199], s[26:27] op_sel_hi:[1,0]
	v_pk_fma_f32 v[98:99], v[98:99], v[166:167], v[198:199]
	v_pk_fma_f32 v[200:201], v[142:143], s[26:27], v[200:201] op_sel:[0,1,0] op_sel_hi:[0,1,1]
	v_pk_mul_f32 v[200:201], v[200:201], v[142:143] op_sel:[0,1] op_sel_hi:[1,1]
	v_pk_fma_f32 v[200:201], v[172:173], v[200:201], v[176:177]
	v_pk_mul_f32 v[200:201], v[200:201], s[26:27] op_sel_hi:[1,0]
	v_pk_fma_f32 v[100:101], v[100:101], v[168:169], v[200:201]
	global_store_dwordx4 v[184:185], v[98:101], off offset:576
	v_lshl_add_u64 v[184:185], v[184:185], 0, s[24:25]
	v_pk_fma_f32 v[202:203], v[144:145], s[26:27], v[202:203] op_sel:[0,1,0] op_sel_hi:[0,1,1]
	v_pk_mul_f32 v[202:203], v[202:203], v[144:145] op_sel:[0,1] op_sel_hi:[1,1]
	v_pk_fma_f32 v[202:203], v[170:171], v[202:203], v[174:175]
	v_pk_mul_f32 v[202:203], v[202:203], s[26:27] op_sel_hi:[1,0]
	v_pk_fma_f32 v[82:83], v[82:83], v[166:167], v[202:203]
	v_pk_fma_f32 v[204:205], v[144:145], s[26:27], v[204:205] op_sel:[0,1,0] op_sel_hi:[0,1,1]
	v_pk_mul_f32 v[204:205], v[204:205], v[144:145] op_sel:[0,1] op_sel_hi:[1,1]
	v_pk_fma_f32 v[204:205], v[172:173], v[204:205], v[176:177]
	v_pk_mul_f32 v[204:205], v[204:205], s[26:27] op_sel_hi:[1,0]
	v_pk_fma_f32 v[84:85], v[84:85], v[168:169], v[204:205]
	global_store_dwordx4 v[184:185], v[82:85], off offset:576
	v_lshl_add_u64 v[184:185], v[184:185], 0, s[24:25]
	v_pk_fma_f32 v[206:207], v[146:147], s[26:27], v[206:207] op_sel:[0,1,0] op_sel_hi:[0,1,1]
	v_pk_mul_f32 v[206:207], v[206:207], v[146:147] op_sel:[0,1] op_sel_hi:[1,1]
	v_pk_fma_f32 v[206:207], v[170:171], v[206:207], v[174:175]
	v_pk_mul_f32 v[206:207], v[206:207], s[26:27] op_sel_hi:[1,0]
	v_pk_fma_f32 v[66:67], v[66:67], v[166:167], v[206:207]
	v_pk_fma_f32 v[208:209], v[146:147], s[26:27], v[208:209] op_sel:[0,1,0] op_sel_hi:[0,1,1]
	v_pk_mul_f32 v[208:209], v[208:209], v[146:147] op_sel:[0,1] op_sel_hi:[1,1]
	v_pk_fma_f32 v[208:209], v[172:173], v[208:209], v[176:177]
	v_pk_mul_f32 v[208:209], v[208:209], s[26:27] op_sel_hi:[1,0]
	v_pk_fma_f32 v[68:69], v[68:69], v[168:169], v[208:209]
	global_store_dwordx4 v[184:185], v[66:69], off offset:576
	s_mov_b64 s[24:25], 0x100000
	v_lshl_add_u64 v[184:185], v[156:157], 0, s[24:25]
	s_mov_b64 s[24:25], 0x20000
	v_pk_fma_f32 v[126:127], v[148:149], s[26:27], v[126:127] op_sel:[0,1,0] op_sel_hi:[0,1,1]
	v_pk_mul_f32 v[126:127], v[126:127], v[148:149] op_sel:[0,1] op_sel_hi:[1,1]
	v_pk_fma_f32 v[126:127], v[170:171], v[126:127], v[174:175]
	v_pk_mul_f32 v[126:127], v[126:127], s[26:27] op_sel_hi:[1,0]
	v_pk_fma_f32 v[50:51], v[50:51], v[166:167], v[126:127]
	v_pk_fma_f32 v[128:129], v[148:149], s[26:27], v[128:129] op_sel:[0,1,0] op_sel_hi:[0,1,1]
	v_pk_mul_f32 v[128:129], v[128:129], v[148:149] op_sel:[0,1] op_sel_hi:[1,1]
	v_pk_fma_f32 v[128:129], v[172:173], v[128:129], v[176:177]
	v_pk_mul_f32 v[128:129], v[128:129], s[26:27] op_sel_hi:[1,0]
	v_pk_fma_f32 v[52:53], v[52:53], v[168:169], v[128:129]
	global_store_dwordx4 v[184:185], v[50:53], off offset:576
	v_lshl_add_u64 v[184:185], v[184:185], 0, s[24:25]
	v_pk_fma_f32 v[110:111], v[150:151], s[26:27], v[110:111] op_sel:[0,1,0] op_sel_hi:[0,1,1]
	v_pk_mul_f32 v[110:111], v[110:111], v[150:151] op_sel:[0,1] op_sel_hi:[1,1]
	v_pk_fma_f32 v[110:111], v[170:171], v[110:111], v[174:175]
	v_pk_mul_f32 v[110:111], v[110:111], s[26:27] op_sel_hi:[1,0]
	v_pk_fma_f32 v[34:35], v[34:35], v[166:167], v[110:111]
	v_pk_fma_f32 v[112:113], v[150:151], s[26:27], v[112:113] op_sel:[0,1,0] op_sel_hi:[0,1,1]
	v_pk_mul_f32 v[112:113], v[112:113], v[150:151] op_sel:[0,1] op_sel_hi:[1,1]
	v_pk_fma_f32 v[112:113], v[172:173], v[112:113], v[176:177]
	v_pk_mul_f32 v[112:113], v[112:113], s[26:27] op_sel_hi:[1,0]
	v_pk_fma_f32 v[36:37], v[36:37], v[168:169], v[112:113]
	global_store_dwordx4 v[184:185], v[34:37], off offset:576
	v_lshl_add_u64 v[184:185], v[184:185], 0, s[24:25]
	v_pk_fma_f32 v[94:95], v[152:153], s[26:27], v[94:95] op_sel:[0,1,0] op_sel_hi:[0,1,1]
	v_pk_mul_f32 v[94:95], v[94:95], v[152:153] op_sel:[0,1] op_sel_hi:[1,1]
	v_pk_fma_f32 v[94:95], v[170:171], v[94:95], v[174:175]
	v_pk_mul_f32 v[94:95], v[94:95], s[26:27] op_sel_hi:[1,0]
	v_pk_fma_f32 v[18:19], v[18:19], v[166:167], v[94:95]
	v_pk_fma_f32 v[96:97], v[152:153], s[26:27], v[96:97] op_sel:[0,1,0] op_sel_hi:[0,1,1]
	v_pk_mul_f32 v[96:97], v[96:97], v[152:153] op_sel:[0,1] op_sel_hi:[1,1]
	v_pk_fma_f32 v[96:97], v[172:173], v[96:97], v[176:177]
	v_pk_mul_f32 v[96:97], v[96:97], s[26:27] op_sel_hi:[1,0]
	v_pk_fma_f32 v[20:21], v[20:21], v[168:169], v[96:97]
	global_store_dwordx4 v[184:185], v[18:21], off offset:576
	v_lshl_add_u64 v[184:185], v[184:185], 0, s[24:25]
	v_pk_fma_f32 v[78:79], v[154:155], s[26:27], v[78:79] op_sel:[0,1,0] op_sel_hi:[0,1,1]
	v_pk_mul_f32 v[78:79], v[78:79], v[154:155] op_sel:[0,1] op_sel_hi:[1,1]
	v_pk_fma_f32 v[78:79], v[170:171], v[78:79], v[174:175]
	v_pk_mul_f32 v[78:79], v[78:79], s[26:27] op_sel_hi:[1,0]
	v_pk_fma_f32 v[2:3], v[2:3], v[166:167], v[78:79]
	v_pk_fma_f32 v[80:81], v[154:155], s[26:27], v[80:81] op_sel:[0,1,0] op_sel_hi:[0,1,1]
	v_pk_mul_f32 v[80:81], v[80:81], v[154:155] op_sel:[0,1] op_sel_hi:[1,1]
	v_pk_fma_f32 v[80:81], v[172:173], v[80:81], v[176:177]
	v_pk_mul_f32 v[80:81], v[80:81], s[26:27] op_sel_hi:[1,0]
	v_pk_fma_f32 v[4:5], v[4:5], v[168:169], v[80:81]
	global_store_dwordx4 v[184:185], v[2:5], off offset:576
	s_and_b64 vcc, exec, s[4:5]
	s_mov_b64 s[24:25], -1
	s_cbranch_vccnz .LBB0_1255
	s_andn2_b64 vcc, exec, s[12:13]
	s_cbranch_vccnz .LBB0_1254
	s_barrier
	s_branch .LBB0_1254
